# attention v8: fewer instructions per step (waits once per two PV MFMAs, single row-sum chain), units ordered by size over the whole per-XCD queue
# speedup vs baseline: 1.0814x; 1.0027x over previous
.LBB0_775:
	s_or_b64 exec, exec, s[4:5]
	s_and_b32 s60, s40, 0xff
	s_lshr_b32 s61, s60, 3
	s_sub_u32 s61, 15, s61
	s_and_b32 s64, s60, 7
	s_lshl_b32 s65, s44, 1
	s_lshl_b32 s45, s61, 2
	s_add_u32 s45, s45, 4
	s_sub_u32 s72, s45, 4
	v_lshrrev_b32_e32 v0, 6, v236
	s_nop 0
	v_readfirstlane_b32 s47, v0
	s_lshl_b32 s66, s64, 22
	s_lshr_b32 s67, s65, 1
	s_lshl_b32 s67, s67, 7
	s_add_u32 s48, s82, 0x9000000
	s_addc_u32 s49, s83, 0
	s_add_u32 s48, s48, s66
	s_addc_u32 s49, s49, 0
	s_add_u32 s48, s48, s67
	s_addc_u32 s49, s49, 0
	s_lshr_b32 s63, s65, 2
	s_lshl_b32 s63, s63, 8
	s_add_u32 s50, s82, 0xb000000
	s_addc_u32 s51, s83, 0
	s_add_u32 s50, s50, s66
	s_addc_u32 s51, s51, 0
	s_add_u32 s50, s50, s63
	s_addc_u32 s51, s51, 0
	s_lshl_b32 s63, s61, 8
	s_lshl_b32 s60, s47, 5
	s_add_u32 s63, s63, s60
	s_lshl_b32 s60, s63, 10
	s_add_u32 s54, s82, 0x7000000
	s_addc_u32 s55, s83, 0
	s_add_u32 s54, s54, s66
	s_addc_u32 s55, s55, 0
	s_add_u32 s54, s54, s60
	s_addc_u32 s55, s55, 0
	s_add_u32 s54, s54, s67
	s_addc_u32 s55, s55, 0
	s_lshl_b32 s60, s64, 12
	s_add_u32 s60, s60, s63
	s_lshl_b32 s60, s60, 11
	s_and_b32 s67, s65, 14
	s_lshl_b32 s67, s67, 7
	s_add_u32 s52, s82, 0x16000000
	s_addc_u32 s53, s83, 0
	s_add_u32 s52, s52, s60
	s_addc_u32 s53, s53, 0
	s_add_u32 s52, s52, s67
	s_addc_u32 s53, s53, 0
	v_and_b32_e32 v237, 63, v236
	v_lshrrev_b32_e32 v252, 5, v237
	v_and_b32_e32 v0, 31, v237
	s_lshl_b32 s60, s47, 4
	v_lshl_add_u32 v238, v237, 10, s60
	s_and_b32 s60, s47, 3
	s_lshl_b32 s60, s60, 14
	s_lshr_b32 s61, s47, 2
	s_lshl_b32 s61, s61, 6
	s_add_u32 s60, s60, s61
	v_lshrrev_b32_e32 v1, 2, v237
	v_lshlrev_b32_e32 v1, 10, v1
	v_and_b32_e32 v2, 3, v237
	v_lshl_or_b32 v1, v2, 4, v1
	v_add_u32_e32 v239, s60, v1
	v_lshlrev_b32_e32 v244, 10, v252
	v_lshl_or_b32 v244, v0, 4, v244
	v_bfe_u32 v1, v237, 4, 1
	v_lshlrev_b32_e32 v1, 5, v1
	v_lshl_or_b32 v1, v2, 3, v1
	v_bfe_u32 v2, v237, 2, 2
	v_lshl_or_b32 v2, v252, 2, v2
	v_lshl_or_b32 v1, v2, 6, v1
	v_add_u32_e32 v245, 24576, v1
	s_lshl_b32 s60, s47, 5
	v_add_u32_e32 v246, s60, v0
	s_lshl_b32 s60, s47, 8
	s_add_u32 s60, s60, 73728
	v_mov_b32_e32 v249, s60
	s_lshl_b32 s70, s47, 10
	s_add_u32 s71, s70, 24576
	s_mov_b64 s[74:75], s[48:49]
	s_mov_b64 s[76:77], s[50:51]
	s_mov_b32 s56, 0x4000
	s_mov_b32 s57, 0
	s_mov_b32 s58, 0x2000
	s_add_i32 m0, s57, s70
	s_nop 0
	global_load_lds_dwordx4 v238, s[74:75]
	s_add_u32 s74, s74, 0x10000
	s_addc_u32 s75, s75, 0
	s_lshl_b32 s60, s57, 1
	s_add_i32 s60, s60, s71
	s_mov_b32 m0, s60
	s_nop 0
	global_load_lds_dwordx4 v239, s[76:77]
	s_add_u32 s62, s76, 0x80
	s_addc_u32 s63, s77, 0
	s_add_i32 m0, s60, 0x2000
	s_nop 0
	global_load_lds_dwordx4 v239, s[62:63]
	s_add_u32 s76, s76, 0x10000
	s_addc_u32 s77, s77, 0
	s_add_i32 m0, s58, s70
	s_nop 0
	global_load_lds_dwordx4 v238, s[74:75]
	s_add_u32 s74, s74, 0x10000
	s_addc_u32 s75, s75, 0
	v_lshlrev_b32_e32 v1, 10, v0
	v_lshl_or_b32 v1, v252, 4, v1
	global_load_dwordx4 v[16:19], v1, s[54:55]
	global_load_dwordx4 v[20:23], v1, s[54:55] offset:32
	global_load_dwordx4 v[24:27], v1, s[54:55] offset:64
	global_load_dwordx4 v[28:31], v1, s[54:55] offset:96
	s_add_i32 m0, s56, s70
	s_nop 0
	global_load_lds_dwordx4 v238, s[74:75]
	s_add_u32 s74, s74, 0x10000
	s_addc_u32 s75, s75, 0
	v_mov_b32_e32 v248, 0
	v_mov_b32_e32 v247, 0
	v_mov_b32_e32 v160, 0
	v_mov_b32_e32 v161, 0
	v_mov_b32_e32 v162, 0
	v_mov_b32_e32 v163, 0
	v_mov_b32_e32 v164, 0
	v_mov_b32_e32 v165, 0
	v_mov_b32_e32 v166, 0
	v_mov_b32_e32 v167, 0
	v_mov_b32_e32 v168, 0
	v_mov_b32_e32 v169, 0
	v_mov_b32_e32 v170, 0
	v_mov_b32_e32 v171, 0
	v_mov_b32_e32 v172, 0
	v_mov_b32_e32 v173, 0
	v_mov_b32_e32 v174, 0
	v_mov_b32_e32 v175, 0
	v_mov_b32_e32 v32, 0
	v_mov_b32_e32 v33, 0
	v_mov_b32_e32 v34, 0
	v_mov_b32_e32 v35, 0
	v_mov_b32_e32 v36, 0
	v_mov_b32_e32 v37, 0
	v_mov_b32_e32 v38, 0
	v_mov_b32_e32 v39, 0
	v_mov_b32_e32 v40, 0
	v_mov_b32_e32 v41, 0
	v_mov_b32_e32 v42, 0
	v_mov_b32_e32 v43, 0
	v_mov_b32_e32 v44, 0
	v_mov_b32_e32 v45, 0
	v_mov_b32_e32 v46, 0
	v_mov_b32_e32 v47, 0
	v_mov_b32_e32 v48, 0
	v_mov_b32_e32 v49, 0
	v_mov_b32_e32 v50, 0
	v_mov_b32_e32 v51, 0
	v_mov_b32_e32 v52, 0
	v_mov_b32_e32 v53, 0
	v_mov_b32_e32 v54, 0
	v_mov_b32_e32 v55, 0
	v_mov_b32_e32 v56, 0
	v_mov_b32_e32 v57, 0
	v_mov_b32_e32 v58, 0
	v_mov_b32_e32 v59, 0
	v_mov_b32_e32 v60, 0
	v_mov_b32_e32 v61, 0
	v_mov_b32_e32 v62, 0
	v_mov_b32_e32 v63, 0
	v_mov_b32_e32 v64, 0
	v_mov_b32_e32 v65, 0
	v_mov_b32_e32 v66, 0
	v_mov_b32_e32 v67, 0
	v_mov_b32_e32 v68, 0
	v_mov_b32_e32 v69, 0
	v_mov_b32_e32 v70, 0
	v_mov_b32_e32 v71, 0
	v_mov_b32_e32 v72, 0
	v_mov_b32_e32 v73, 0
	v_mov_b32_e32 v74, 0
	v_mov_b32_e32 v75, 0
	v_mov_b32_e32 v76, 0
	v_mov_b32_e32 v77, 0
	v_mov_b32_e32 v78, 0
	v_mov_b32_e32 v79, 0
	v_mov_b32_e32 v80, 0
	v_mov_b32_e32 v81, 0
	v_mov_b32_e32 v82, 0
	v_mov_b32_e32 v83, 0
	v_mov_b32_e32 v84, 0
	v_mov_b32_e32 v85, 0
	v_mov_b32_e32 v86, 0
	v_mov_b32_e32 v87, 0
	v_mov_b32_e32 v88, 0
	v_mov_b32_e32 v89, 0
	v_mov_b32_e32 v90, 0
	v_mov_b32_e32 v91, 0
	v_mov_b32_e32 v92, 0
	v_mov_b32_e32 v93, 0
	v_mov_b32_e32 v94, 0
	v_mov_b32_e32 v95, 0
	s_mov_b32 s46, 0
	s_waitcnt vmcnt(8) lgkmcnt(0)
	s_barrier
	v_add_u32_e32 v250, s57, v244
	ds_read_b128 v[208:211], v250
	ds_read_b128 v[212:215], v250 offset:512
	ds_read_b128 v[216:219], v250 offset:2048
	ds_read_b128 v[220:223], v250 offset:2560
	ds_read_b128 v[224:227], v250 offset:4096
	ds_read_b128 v[228:231], v250 offset:4608
	ds_read_b128 v[232:235], v250 offset:6144
	ds_read_b128 v[240:243], v250 offset:6656
	s_waitcnt vmcnt(1) lgkmcnt(0)
	v_mfma_f32_32x32x16_bf16 v[96:111], v[208:211], v[16:19], v[160:175]
	v_mfma_f32_32x32x16_bf16 v[112:127], v[212:215], v[16:19], v[160:175]
	v_mfma_f32_32x32x16_bf16 v[96:111], v[216:219], v[20:23], v[96:111]
	v_mfma_f32_32x32x16_bf16 v[112:127], v[220:223], v[20:23], v[112:127]
	v_mfma_f32_32x32x16_bf16 v[96:111], v[224:227], v[24:27], v[96:111]
	v_mfma_f32_32x32x16_bf16 v[112:127], v[228:231], v[24:27], v[112:127]
	v_mfma_f32_32x32x16_bf16 v[96:111], v[232:235], v[28:31], v[96:111]
	v_mfma_f32_32x32x16_bf16 v[112:127], v[240:243], v[28:31], v[112:127]
	s_nop 7
	s_nop 7
	s_cmp_lt_u32 s46, s72
	s_cbranch_scc1 .Lat_nomask_226
	s_sub_u32 s60, s46, s72
	s_lshl_b32 s60, s60, 6
	v_lshl_add_u32 v0, v252, 2, s60
	v_sub_u32_e32 v0, v246, v0
	v_mov_b32_e32 v1, 0xff800000
	v_cmp_gt_i32_e64 s[60:61], 0, v0
	v_cmp_gt_i32_e64 s[62:63], 32, v0
	v_cmp_gt_i32_e64 s[64:65], 1, v0
	v_cmp_gt_i32_e64 s[66:67], 33, v0
	v_cndmask_b32_e64 v96, v96, v1, s[60:61]
	v_cmp_gt_i32_e64 s[60:61], 2, v0
	v_cndmask_b32_e64 v112, v112, v1, s[62:63]
	v_cmp_gt_i32_e64 s[62:63], 34, v0
	v_cndmask_b32_e64 v97, v97, v1, s[64:65]
	v_cmp_gt_i32_e64 s[64:65], 3, v0
	v_cndmask_b32_e64 v113, v113, v1, s[66:67]
	v_cmp_gt_i32_e64 s[66:67], 35, v0
	v_cndmask_b32_e64 v98, v98, v1, s[60:61]
	v_cmp_gt_i32_e64 s[60:61], 8, v0
	v_cndmask_b32_e64 v114, v114, v1, s[62:63]
	v_cmp_gt_i32_e64 s[62:63], 40, v0
	v_cndmask_b32_e64 v99, v99, v1, s[64:65]
	v_cmp_gt_i32_e64 s[64:65], 9, v0
	v_cndmask_b32_e64 v115, v115, v1, s[66:67]
	v_cmp_gt_i32_e64 s[66:67], 41, v0
	v_cndmask_b32_e64 v100, v100, v1, s[60:61]
	v_cmp_gt_i32_e64 s[60:61], 10, v0
	v_cndmask_b32_e64 v116, v116, v1, s[62:63]
	v_cmp_gt_i32_e64 s[62:63], 42, v0
	v_cndmask_b32_e64 v101, v101, v1, s[64:65]
	v_cmp_gt_i32_e64 s[64:65], 11, v0
	v_cndmask_b32_e64 v117, v117, v1, s[66:67]
	v_cmp_gt_i32_e64 s[66:67], 43, v0
	v_cndmask_b32_e64 v102, v102, v1, s[60:61]
	v_cmp_gt_i32_e64 s[60:61], 16, v0
	v_cndmask_b32_e64 v118, v118, v1, s[62:63]
	v_cmp_gt_i32_e64 s[62:63], 48, v0
	v_cndmask_b32_e64 v103, v103, v1, s[64:65]
	v_cmp_gt_i32_e64 s[64:65], 17, v0
	v_cndmask_b32_e64 v119, v119, v1, s[66:67]
	v_cmp_gt_i32_e64 s[66:67], 49, v0
	v_cndmask_b32_e64 v104, v104, v1, s[60:61]
	v_cmp_gt_i32_e64 s[60:61], 18, v0
	v_cndmask_b32_e64 v120, v120, v1, s[62:63]
	v_cmp_gt_i32_e64 s[62:63], 50, v0
	v_cndmask_b32_e64 v105, v105, v1, s[64:65]
	v_cmp_gt_i32_e64 s[64:65], 19, v0
	v_cndmask_b32_e64 v121, v121, v1, s[66:67]
	v_cmp_gt_i32_e64 s[66:67], 51, v0
	v_cndmask_b32_e64 v106, v106, v1, s[60:61]
	v_cmp_gt_i32_e64 s[60:61], 24, v0
	v_cndmask_b32_e64 v122, v122, v1, s[62:63]
	v_cmp_gt_i32_e64 s[62:63], 56, v0
	v_cndmask_b32_e64 v107, v107, v1, s[64:65]
	v_cmp_gt_i32_e64 s[64:65], 25, v0
	v_cndmask_b32_e64 v123, v123, v1, s[66:67]
	v_cmp_gt_i32_e64 s[66:67], 57, v0
	v_cndmask_b32_e64 v108, v108, v1, s[60:61]
	v_cmp_gt_i32_e64 s[60:61], 26, v0
	v_cndmask_b32_e64 v124, v124, v1, s[62:63]
	v_cmp_gt_i32_e64 s[62:63], 58, v0
	v_cndmask_b32_e64 v109, v109, v1, s[64:65]
	v_cmp_gt_i32_e64 s[64:65], 27, v0
	v_cndmask_b32_e64 v125, v125, v1, s[66:67]
	v_cmp_gt_i32_e64 s[66:67], 59, v0
	v_cndmask_b32_e64 v110, v110, v1, s[60:61]
	s_nop 1
	v_cndmask_b32_e64 v126, v126, v1, s[62:63]
	v_cndmask_b32_e64 v111, v111, v1, s[64:65]
	v_cndmask_b32_e64 v127, v127, v1, s[66:67]

.Lat_loop:
	s_cmp_ge_u32 s46, s45
	s_cbranch_scc1 .Lat_drain
	s_lshl_b32 s60, s56, 1
	v_add_u32_e32 v250, s60, v245
	v_mfma_f32_32x32x16_bf16 v[128:143], v[208:211], v[16:19], v[160:175]
	v_add_f32_e32 v247, v247, v96
	v_add_f32_e32 v247, v247, v97
	v_add_f32_e32 v247, v247, v98
	v_add_f32_e32 v247, v247, v99
	v_cvt_pk_bf16_f32 v176, v96, v97
	v_cvt_pk_bf16_f32 v177, v98, v99
	v_mfma_f32_32x32x16_bf16 v[144:159], v[212:215], v[16:19], v[160:175]
	v_add_f32_e32 v247, v247, v100
	v_add_f32_e32 v247, v247, v101
	v_add_f32_e32 v247, v247, v102
	v_add_f32_e32 v247, v247, v103
	v_cvt_pk_bf16_f32 v178, v100, v101
	v_cvt_pk_bf16_f32 v179, v102, v103
	v_mfma_f32_32x32x16_bf16 v[128:143], v[216:219], v[20:23], v[128:143]
	v_add_f32_e32 v247, v247, v104
	v_add_f32_e32 v247, v247, v105
	v_add_f32_e32 v247, v247, v106
	v_add_f32_e32 v247, v247, v107
	v_cvt_pk_bf16_f32 v180, v104, v105
	v_cvt_pk_bf16_f32 v181, v106, v107
	v_mfma_f32_32x32x16_bf16 v[144:159], v[220:223], v[20:23], v[144:159]
	v_add_f32_e32 v247, v247, v108
	v_add_f32_e32 v247, v247, v109
	v_add_f32_e32 v247, v247, v110
	v_add_f32_e32 v247, v247, v111
	v_cvt_pk_bf16_f32 v182, v108, v109
	v_cvt_pk_bf16_f32 v183, v110, v111
	v_mfma_f32_32x32x16_bf16 v[128:143], v[224:227], v[24:27], v[128:143]
	v_add_f32_e32 v247, v247, v112
	v_add_f32_e32 v247, v247, v113
	v_add_f32_e32 v247, v247, v114
	v_add_f32_e32 v247, v247, v115
	v_cvt_pk_bf16_f32 v184, v112, v113
	v_cvt_pk_bf16_f32 v185, v114, v115
	v_mfma_f32_32x32x16_bf16 v[144:159], v[228:231], v[24:27], v[144:159]
	v_add_f32_e32 v247, v247, v116
	v_add_f32_e32 v247, v247, v117
	v_add_f32_e32 v247, v247, v118
	v_add_f32_e32 v247, v247, v119
	v_cvt_pk_bf16_f32 v186, v116, v117
	v_cvt_pk_bf16_f32 v187, v118, v119
	v_mfma_f32_32x32x16_bf16 v[128:143], v[232:235], v[28:31], v[128:143]
	v_add_f32_e32 v247, v247, v120
	v_add_f32_e32 v247, v247, v121
	v_add_f32_e32 v247, v247, v122
	v_add_f32_e32 v247, v247, v123
	v_cvt_pk_bf16_f32 v188, v120, v121
	v_cvt_pk_bf16_f32 v189, v122, v123
	ds_read_b64_tr_b16 v[192:193], v250 offset:0
	ds_read_b64_tr_b16 v[194:195], v250 offset:512
	v_mfma_f32_32x32x16_bf16 v[144:159], v[240:243], v[28:31], v[144:159]
	v_add_f32_e32 v247, v247, v124
	v_add_f32_e32 v247, v247, v125
	v_add_f32_e32 v247, v247, v126
	v_add_f32_e32 v247, v247, v127
	v_cvt_pk_bf16_f32 v190, v124, v125
	v_cvt_pk_bf16_f32 v191, v126, v127
	ds_read_b64_tr_b16 v[196:197], v250 offset:4096
	ds_read_b64_tr_b16 v[198:199], v250 offset:4608
	s_add_i32 m0, s57, s70
	s_nop 0
	global_load_lds_dwordx4 v238, s[74:75]
	s_add_u32 s74, s74, 0x10000
	s_addc_u32 s75, s75, 0
	s_lshl_b32 s60, s58, 1
	s_add_i32 s60, s60, s71
	s_mov_b32 m0, s60
	s_nop 0
	global_load_lds_dwordx4 v239, s[76:77]
	s_add_u32 s62, s76, 0x80
	s_addc_u32 s63, s77, 0
	s_add_i32 m0, s60, 0x2000
	s_nop 0
	global_load_lds_dwordx4 v239, s[62:63]
	s_add_u32 s76, s76, 0x10000
	s_addc_u32 s77, s77, 0
	s_cmp_lt_u32 s46, s72
	s_cbranch_scc1 .Lat_nomask_520
	s_sub_u32 s60, s46, s72
	s_lshl_b32 s60, s60, 6
	v_lshl_add_u32 v0, v252, 2, s60
	v_sub_u32_e32 v0, v246, v0
	v_mov_b32_e32 v1, 0xff800000
	v_cmp_gt_i32_e64 s[60:61], 0, v0
	v_cmp_gt_i32_e64 s[62:63], 32, v0
	v_cmp_gt_i32_e64 s[64:65], 1, v0
	v_cmp_gt_i32_e64 s[66:67], 33, v0
	v_cndmask_b32_e64 v128, v128, v1, s[60:61]
	v_cmp_gt_i32_e64 s[60:61], 2, v0
	v_cndmask_b32_e64 v144, v144, v1, s[62:63]
	v_cmp_gt_i32_e64 s[62:63], 34, v0
	v_cndmask_b32_e64 v129, v129, v1, s[64:65]
	v_cmp_gt_i32_e64 s[64:65], 3, v0
	v_cndmask_b32_e64 v145, v145, v1, s[66:67]
	v_cmp_gt_i32_e64 s[66:67], 35, v0
	v_cndmask_b32_e64 v130, v130, v1, s[60:61]
	v_cmp_gt_i32_e64 s[60:61], 8, v0
	v_cndmask_b32_e64 v146, v146, v1, s[62:63]
	v_cmp_gt_i32_e64 s[62:63], 40, v0
	v_cndmask_b32_e64 v131, v131, v1, s[64:65]
	v_cmp_gt_i32_e64 s[64:65], 9, v0
	v_cndmask_b32_e64 v147, v147, v1, s[66:67]
	v_cmp_gt_i32_e64 s[66:67], 41, v0
	v_cndmask_b32_e64 v132, v132, v1, s[60:61]
	v_cmp_gt_i32_e64 s[60:61], 10, v0
	v_cndmask_b32_e64 v148, v148, v1, s[62:63]
	v_cmp_gt_i32_e64 s[62:63], 42, v0
	v_cndmask_b32_e64 v133, v133, v1, s[64:65]
	v_cmp_gt_i32_e64 s[64:65], 11, v0
	v_cndmask_b32_e64 v149, v149, v1, s[66:67]
	v_cmp_gt_i32_e64 s[66:67], 43, v0
	v_cndmask_b32_e64 v134, v134, v1, s[60:61]
	v_cmp_gt_i32_e64 s[60:61], 16, v0
	v_cndmask_b32_e64 v150, v150, v1, s[62:63]
	v_cmp_gt_i32_e64 s[62:63], 48, v0
	v_cndmask_b32_e64 v135, v135, v1, s[64:65]
	v_cmp_gt_i32_e64 s[64:65], 17, v0
	v_cndmask_b32_e64 v151, v151, v1, s[66:67]
	v_cmp_gt_i32_e64 s[66:67], 49, v0
	v_cndmask_b32_e64 v136, v136, v1, s[60:61]
	v_cmp_gt_i32_e64 s[60:61], 18, v0
	v_cndmask_b32_e64 v152, v152, v1, s[62:63]
	v_cmp_gt_i32_e64 s[62:63], 50, v0
	v_cndmask_b32_e64 v137, v137, v1, s[64:65]
	v_cmp_gt_i32_e64 s[64:65], 19, v0
	v_cndmask_b32_e64 v153, v153, v1, s[66:67]
	v_cmp_gt_i32_e64 s[66:67], 51, v0
	v_cndmask_b32_e64 v138, v138, v1, s[60:61]
	v_cmp_gt_i32_e64 s[60:61], 24, v0
	v_cndmask_b32_e64 v154, v154, v1, s[62:63]
	v_cmp_gt_i32_e64 s[62:63], 56, v0
	v_cndmask_b32_e64 v139, v139, v1, s[64:65]
	v_cmp_gt_i32_e64 s[64:65], 25, v0
	v_cndmask_b32_e64 v155, v155, v1, s[66:67]
	v_cmp_gt_i32_e64 s[66:67], 57, v0
	v_cndmask_b32_e64 v140, v140, v1, s[60:61]
	v_cmp_gt_i32_e64 s[60:61], 26, v0
	v_cndmask_b32_e64 v156, v156, v1, s[62:63]
	v_cmp_gt_i32_e64 s[62:63], 58, v0
	v_cndmask_b32_e64 v141, v141, v1, s[64:65]
	v_cmp_gt_i32_e64 s[64:65], 27, v0
	v_cndmask_b32_e64 v157, v157, v1, s[66:67]
	v_cmp_gt_i32_e64 s[66:67], 59, v0
	v_cndmask_b32_e64 v142, v142, v1, s[60:61]
	s_nop 1
	v_cndmask_b32_e64 v158, v158, v1, s[62:63]
	v_cndmask_b32_e64 v143, v143, v1, s[64:65]
	v_cndmask_b32_e64 v159, v159, v1, s[66:67]
.Lat_nomask_520:
	ds_read_b64_tr_b16 v[200:201], v250 offset:8192
	ds_read_b64_tr_b16 v[202:203], v250 offset:8704
	ds_read_b64_tr_b16 v[204:205], v250 offset:12288
	ds_read_b64_tr_b16 v[206:207], v250 offset:12800
	s_waitcnt lgkmcnt(4)
	v_mfma_f32_32x32x16_bf16 v[32:47], v[176:179], v[192:195], v[32:47]
	v_max3_f32 v2, v128, v129, v144
	v_max3_f32 v4, v130, v131, v145
	v_max3_f32 v2, v2, v146, v147
	v_mfma_f32_32x32x16_bf16 v[48:63], v[176:179], v[196:199], v[48:63]
	v_max3_f32 v2, v2, v132, v133
	v_max3_f32 v4, v4, v134, v135
	v_max3_f32 v2, v2, v148, v149
	ds_read_b64_tr_b16 v[192:193], v250 offset:1024
	ds_read_b64_tr_b16 v[194:195], v250 offset:1536
	ds_read_b64_tr_b16 v[196:197], v250 offset:5120
	ds_read_b64_tr_b16 v[198:199], v250 offset:5632
	s_waitcnt lgkmcnt(4)
	v_mfma_f32_32x32x16_bf16 v[64:79], v[176:179], v[200:203], v[64:79]
	v_max3_f32 v4, v4, v150, v151
	v_max3_f32 v2, v2, v136, v137
	v_max3_f32 v4, v4, v138, v139
	v_mfma_f32_32x32x16_bf16 v[80:95], v[176:179], v[204:207], v[80:95]
	v_max3_f32 v2, v2, v152, v153
	v_max3_f32 v4, v4, v154, v155
	v_max3_f32 v2, v2, v140, v141
	ds_read_b64_tr_b16 v[200:201], v250 offset:9216
	ds_read_b64_tr_b16 v[202:203], v250 offset:9728
	ds_read_b64_tr_b16 v[204:205], v250 offset:13312
	ds_read_b64_tr_b16 v[206:207], v250 offset:13824
	s_waitcnt lgkmcnt(4)
	v_mfma_f32_32x32x16_bf16 v[32:47], v[180:183], v[192:195], v[32:47]
	v_max3_f32 v4, v4, v142, v143
	v_max3_f32 v2, v2, v156, v157
	v_max3_f32 v4, v4, v158, v159
	v_mfma_f32_32x32x16_bf16 v[48:63], v[180:183], v[196:199], v[48:63]
	v_max_f32_e32 v2, v2, v4
	v_mov_b32_e32 v4, v2
	s_nop 1
	v_permlane32_swap_b32_e32 v2, v4
	v_max_f32_e32 v2, v2, v4
	v_mov_b32_e32 v5, 0x41400000
	v_cmp_gt_f32_e32 vcc, v2, v5
	s_mov_b64 s[68:69], vcc
	s_cmp_lg_u64 vcc, 0
	s_cbranch_scc0 .Lat_noresc_439
	v_max_f32_e32 v4, 0, v2
	v_add_f32_e32 v248, v248, v4
	v_sub_f32_e32 v128, v128, v4
	v_sub_f32_e32 v129, v129, v4
	v_sub_f32_e32 v130, v130, v4
	v_sub_f32_e32 v131, v131, v4
	v_sub_f32_e32 v132, v132, v4
	v_sub_f32_e32 v133, v133, v4
	v_sub_f32_e32 v134, v134, v4
	v_sub_f32_e32 v135, v135, v4
	v_sub_f32_e32 v136, v136, v4
	v_sub_f32_e32 v137, v137, v4
	v_sub_f32_e32 v138, v138, v4
	v_sub_f32_e32 v139, v139, v4
	v_sub_f32_e32 v140, v140, v4
	v_sub_f32_e32 v141, v141, v4
	v_sub_f32_e32 v142, v142, v4
	v_sub_f32_e32 v143, v143, v4
	v_sub_f32_e32 v144, v144, v4
	v_sub_f32_e32 v145, v145, v4
	v_sub_f32_e32 v146, v146, v4
	v_sub_f32_e32 v147, v147, v4
	v_sub_f32_e32 v148, v148, v4
	v_sub_f32_e32 v149, v149, v4
	v_sub_f32_e32 v150, v150, v4
	v_sub_f32_e32 v151, v151, v4
	v_sub_f32_e32 v152, v152, v4
	v_sub_f32_e32 v153, v153, v4
	v_sub_f32_e32 v154, v154, v4
	v_sub_f32_e32 v155, v155, v4
	v_sub_f32_e32 v156, v156, v4
	v_sub_f32_e32 v157, v157, v4
	v_sub_f32_e32 v158, v158, v4
	v_sub_f32_e32 v159, v159, v4
	v_xor_b32_e32 v5, 0x80000000, v248
	v_mov_b32_e32 v160, v5
	v_mov_b32_e32 v161, v5
	v_mov_b32_e32 v162, v5
	v_mov_b32_e32 v163, v5
	v_mov_b32_e32 v164, v5
	v_mov_b32_e32 v165, v5
	v_mov_b32_e32 v166, v5
	v_mov_b32_e32 v167, v5
	v_mov_b32_e32 v168, v5
	v_mov_b32_e32 v169, v5
	v_mov_b32_e32 v170, v5
	v_mov_b32_e32 v171, v5
	v_mov_b32_e32 v172, v5
	v_mov_b32_e32 v173, v5
	v_mov_b32_e32 v174, v5
	v_mov_b32_e32 v175, v5
	v_xor_b32_e32 v6, 0x80000000, v4
	v_exp_f32_e32 v6, v6
	s_nop 0
	v_mul_f32_e32 v247, v247, v6
	v_and_b32_e32 v7, 31, v237
	v_lshl_add_u32 v7, v7, 2, v249
	v_cmp_eq_u32_e32 vcc, 0, v252
	s_and_saveexec_b64 s[60:61], vcc
	ds_write_b32 v7, v6
	s_or_b64 exec, exec, s[60:61]
.Lat_noresc_439:
	v_add_u32_e32 v3, s58, v244
	ds_read_b64_tr_b16 v[192:193], v250 offset:2048
	ds_read_b64_tr_b16 v[194:195], v250 offset:2560
	ds_read_b64_tr_b16 v[196:197], v250 offset:6144
	ds_read_b64_tr_b16 v[198:199], v250 offset:6656
	s_waitcnt lgkmcnt(4)
	v_mfma_f32_32x32x16_bf16 v[64:79], v[180:183], v[200:203], v[64:79]
	v_exp_f32_e32 v128, v128
	v_exp_f32_e32 v129, v129
	v_exp_f32_e32 v130, v130
	ds_read_b128 v[208:211], v3
	v_mfma_f32_32x32x16_bf16 v[80:95], v[180:183], v[204:207], v[80:95]
	v_exp_f32_e32 v131, v131
	v_exp_f32_e32 v132, v132
	v_exp_f32_e32 v133, v133
	ds_read_b128 v[212:215], v3 offset:512
	ds_read_b64_tr_b16 v[200:201], v250 offset:10240
	ds_read_b64_tr_b16 v[202:203], v250 offset:10752
	ds_read_b64_tr_b16 v[204:205], v250 offset:14336
	ds_read_b64_tr_b16 v[206:207], v250 offset:14848
	s_waitcnt lgkmcnt(6)
	v_mfma_f32_32x32x16_bf16 v[32:47], v[184:187], v[192:195], v[32:47]
	v_exp_f32_e32 v134, v134
	v_exp_f32_e32 v135, v135
	v_exp_f32_e32 v136, v136
	ds_read_b128 v[216:219], v3 offset:2048
	v_mfma_f32_32x32x16_bf16 v[48:63], v[184:187], v[196:199], v[48:63]
	v_exp_f32_e32 v137, v137
	v_exp_f32_e32 v138, v138
	v_exp_f32_e32 v139, v139
	ds_read_b128 v[220:223], v3 offset:2560
	ds_read_b64_tr_b16 v[192:193], v250 offset:3072
	ds_read_b64_tr_b16 v[194:195], v250 offset:3584
	ds_read_b64_tr_b16 v[196:197], v250 offset:7168
	ds_read_b64_tr_b16 v[198:199], v250 offset:7680
	s_waitcnt lgkmcnt(6)
	v_mfma_f32_32x32x16_bf16 v[64:79], v[184:187], v[200:203], v[64:79]
	v_exp_f32_e32 v140, v140
	v_exp_f32_e32 v141, v141
	v_exp_f32_e32 v142, v142
	ds_read_b128 v[224:227], v3 offset:4096
	v_mfma_f32_32x32x16_bf16 v[80:95], v[184:187], v[204:207], v[80:95]
	v_exp_f32_e32 v143, v143
	v_exp_f32_e32 v144, v144
	v_exp_f32_e32 v145, v145
	ds_read_b128 v[228:231], v3 offset:4608
	ds_read_b64_tr_b16 v[200:201], v250 offset:11264
	ds_read_b64_tr_b16 v[202:203], v250 offset:11776
	ds_read_b64_tr_b16 v[204:205], v250 offset:15360
	ds_read_b64_tr_b16 v[206:207], v250 offset:15872
	s_waitcnt lgkmcnt(6)
	v_mfma_f32_32x32x16_bf16 v[32:47], v[188:191], v[192:195], v[32:47]
	v_exp_f32_e32 v146, v146
	v_exp_f32_e32 v147, v147
	v_exp_f32_e32 v148, v148
	ds_read_b128 v[232:235], v3 offset:6144
	v_mfma_f32_32x32x16_bf16 v[48:63], v[188:191], v[196:199], v[48:63]
	v_exp_f32_e32 v149, v149
	v_exp_f32_e32 v150, v150
	v_exp_f32_e32 v151, v151
	ds_read_b128 v[240:243], v3 offset:6656
	s_waitcnt lgkmcnt(2)
	v_mfma_f32_32x32x16_bf16 v[64:79], v[188:191], v[200:203], v[64:79]
	v_exp_f32_e32 v152, v152
	v_exp_f32_e32 v153, v153
	v_exp_f32_e32 v154, v154
	v_exp_f32_e32 v155, v155
	v_mfma_f32_32x32x16_bf16 v[80:95], v[188:191], v[204:207], v[80:95]
	v_exp_f32_e32 v156, v156
	v_exp_f32_e32 v157, v157
	v_exp_f32_e32 v158, v158
	v_exp_f32_e32 v159, v159
	s_waitcnt vmcnt(3) lgkmcnt(0)
	s_barrier
	s_cmp_lg_u64 s[68:69], 0
	s_cbranch_scc0 .Lat_norescO_439
	v_lshl_add_u32 v250, v252, 4, v249
	ds_read_b128 v[0:3], v250 offset:0
	ds_read_b128 v[4:7], v250 offset:32
	ds_read_b128 v[8:11], v250 offset:64
	ds_read_b128 v[12:15], v250 offset:96
	s_nop 7
	s_nop 7
	s_waitcnt lgkmcnt(0)
	v_mul_f32_e32 v32, v32, v0
	v_mul_f32_e32 v33, v33, v1
	v_mul_f32_e32 v34, v34, v2
	v_mul_f32_e32 v35, v35, v3
	v_mul_f32_e32 v36, v36, v4
	v_mul_f32_e32 v37, v37, v5
	v_mul_f32_e32 v38, v38, v6
	v_mul_f32_e32 v39, v39, v7
	v_mul_f32_e32 v40, v40, v8
	v_mul_f32_e32 v41, v41, v9
	v_mul_f32_e32 v42, v42, v10
	v_mul_f32_e32 v43, v43, v11
	v_mul_f32_e32 v44, v44, v12
	v_mul_f32_e32 v45, v45, v13
	v_mul_f32_e32 v46, v46, v14
	v_mul_f32_e32 v47, v47, v15
	v_mul_f32_e32 v48, v48, v0
	v_mul_f32_e32 v49, v49, v1
	v_mul_f32_e32 v50, v50, v2
	v_mul_f32_e32 v51, v51, v3
	v_mul_f32_e32 v52, v52, v4
	v_mul_f32_e32 v53, v53, v5
	v_mul_f32_e32 v54, v54, v6
	v_mul_f32_e32 v55, v55, v7
	v_mul_f32_e32 v56, v56, v8
	v_mul_f32_e32 v57, v57, v9
	v_mul_f32_e32 v58, v58, v10
	v_mul_f32_e32 v59, v59, v11
	v_mul_f32_e32 v60, v60, v12
	v_mul_f32_e32 v61, v61, v13
	v_mul_f32_e32 v62, v62, v14
	v_mul_f32_e32 v63, v63, v15
	v_mul_f32_e32 v64, v64, v0
	v_mul_f32_e32 v65, v65, v1
	v_mul_f32_e32 v66, v66, v2
	v_mul_f32_e32 v67, v67, v3
	v_mul_f32_e32 v68, v68, v4
	v_mul_f32_e32 v69, v69, v5
	v_mul_f32_e32 v70, v70, v6
	v_mul_f32_e32 v71, v71, v7
	v_mul_f32_e32 v72, v72, v8
	v_mul_f32_e32 v73, v73, v9
	v_mul_f32_e32 v74, v74, v10
	v_mul_f32_e32 v75, v75, v11
	v_mul_f32_e32 v76, v76, v12
	v_mul_f32_e32 v77, v77, v13
	v_mul_f32_e32 v78, v78, v14
	v_mul_f32_e32 v79, v79, v15
	v_mul_f32_e32 v80, v80, v0
	v_mul_f32_e32 v81, v81, v1
	v_mul_f32_e32 v82, v82, v2
	v_mul_f32_e32 v83, v83, v3
	v_mul_f32_e32 v84, v84, v4
	v_mul_f32_e32 v85, v85, v5
	v_mul_f32_e32 v86, v86, v6
	v_mul_f32_e32 v87, v87, v7
	v_mul_f32_e32 v88, v88, v8
	v_mul_f32_e32 v89, v89, v9
	v_mul_f32_e32 v90, v90, v10
	v_mul_f32_e32 v91, v91, v11
	v_mul_f32_e32 v92, v92, v12
	v_mul_f32_e32 v93, v93, v13
	v_mul_f32_e32 v94, v94, v14
	v_mul_f32_e32 v95, v95, v15
.Lat_norescO_439:
	s_mov_b32 s67, s56
	s_mov_b32 s56, s57
	s_mov_b32 s57, s58
	s_mov_b32 s58, s67
	s_add_u32 s46, s46, 1
	s_cmp_ge_u32 s46, s45
	s_cbranch_scc1 .Lat_drain
	s_lshl_b32 s60, s56, 1
	v_add_u32_e32 v250, s60, v245
	v_mfma_f32_32x32x16_bf16 v[96:111], v[208:211], v[16:19], v[160:175]
	v_add_f32_e32 v247, v247, v128
	v_add_f32_e32 v247, v247, v129
	v_add_f32_e32 v247, v247, v130
	v_add_f32_e32 v247, v247, v131
	v_cvt_pk_bf16_f32 v176, v128, v129
	v_cvt_pk_bf16_f32 v177, v130, v131
	v_mfma_f32_32x32x16_bf16 v[112:127], v[212:215], v[16:19], v[160:175]
	v_add_f32_e32 v247, v247, v132
	v_add_f32_e32 v247, v247, v133
	v_add_f32_e32 v247, v247, v134
	v_add_f32_e32 v247, v247, v135
	v_cvt_pk_bf16_f32 v178, v132, v133
	v_cvt_pk_bf16_f32 v179, v134, v135
	v_mfma_f32_32x32x16_bf16 v[96:111], v[216:219], v[20:23], v[96:111]
	v_add_f32_e32 v247, v247, v136
	v_add_f32_e32 v247, v247, v137
	v_add_f32_e32 v247, v247, v138
	v_add_f32_e32 v247, v247, v139
	v_cvt_pk_bf16_f32 v180, v136, v137
	v_cvt_pk_bf16_f32 v181, v138, v139
	v_mfma_f32_32x32x16_bf16 v[112:127], v[220:223], v[20:23], v[112:127]
	v_add_f32_e32 v247, v247, v140
	v_add_f32_e32 v247, v247, v141
	v_add_f32_e32 v247, v247, v142
	v_add_f32_e32 v247, v247, v143
	v_cvt_pk_bf16_f32 v182, v140, v141
	v_cvt_pk_bf16_f32 v183, v142, v143
	v_mfma_f32_32x32x16_bf16 v[96:111], v[224:227], v[24:27], v[96:111]
	v_add_f32_e32 v247, v247, v144
	v_add_f32_e32 v247, v247, v145
	v_add_f32_e32 v247, v247, v146
	v_add_f32_e32 v247, v247, v147
	v_cvt_pk_bf16_f32 v184, v144, v145
	v_cvt_pk_bf16_f32 v185, v146, v147
	v_mfma_f32_32x32x16_bf16 v[112:127], v[228:231], v[24:27], v[112:127]
	v_add_f32_e32 v247, v247, v148
	v_add_f32_e32 v247, v247, v149
	v_add_f32_e32 v247, v247, v150
	v_add_f32_e32 v247, v247, v151
	v_cvt_pk_bf16_f32 v186, v148, v149
	v_cvt_pk_bf16_f32 v187, v150, v151
	v_mfma_f32_32x32x16_bf16 v[96:111], v[232:235], v[28:31], v[96:111]
	v_add_f32_e32 v247, v247, v152
	v_add_f32_e32 v247, v247, v153
	v_add_f32_e32 v247, v247, v154
	v_add_f32_e32 v247, v247, v155
	v_cvt_pk_bf16_f32 v188, v152, v153
	v_cvt_pk_bf16_f32 v189, v154, v155
	ds_read_b64_tr_b16 v[192:193], v250 offset:0
	ds_read_b64_tr_b16 v[194:195], v250 offset:512
	v_mfma_f32_32x32x16_bf16 v[112:127], v[240:243], v[28:31], v[112:127]
	v_add_f32_e32 v247, v247, v156
	v_add_f32_e32 v247, v247, v157
	v_add_f32_e32 v247, v247, v158
	v_add_f32_e32 v247, v247, v159
	v_cvt_pk_bf16_f32 v190, v156, v157
	v_cvt_pk_bf16_f32 v191, v158, v159
	ds_read_b64_tr_b16 v[196:197], v250 offset:4096
	ds_read_b64_tr_b16 v[198:199], v250 offset:4608
	s_add_i32 m0, s57, s70
	s_nop 0
	global_load_lds_dwordx4 v238, s[74:75]
	s_add_u32 s74, s74, 0x10000
	s_addc_u32 s75, s75, 0
	s_lshl_b32 s60, s58, 1
	s_add_i32 s60, s60, s71
	s_mov_b32 m0, s60
	s_nop 0
	global_load_lds_dwordx4 v239, s[76:77]
	s_add_u32 s62, s76, 0x80
	s_addc_u32 s63, s77, 0
	s_add_i32 m0, s60, 0x2000
	s_nop 0
	global_load_lds_dwordx4 v239, s[62:63]
	s_add_u32 s76, s76, 0x10000
	s_addc_u32 s77, s77, 0
	s_cmp_lt_u32 s46, s72
	s_cbranch_scc1 .Lat_nomask_936
	s_sub_u32 s60, s46, s72
	s_lshl_b32 s60, s60, 6
	v_lshl_add_u32 v0, v252, 2, s60
	v_sub_u32_e32 v0, v246, v0
	v_mov_b32_e32 v1, 0xff800000
	v_cmp_gt_i32_e64 s[60:61], 0, v0
	v_cmp_gt_i32_e64 s[62:63], 32, v0
	v_cmp_gt_i32_e64 s[64:65], 1, v0
	v_cmp_gt_i32_e64 s[66:67], 33, v0
	v_cndmask_b32_e64 v96, v96, v1, s[60:61]
	v_cmp_gt_i32_e64 s[60:61], 2, v0
	v_cndmask_b32_e64 v112, v112, v1, s[62:63]
	v_cmp_gt_i32_e64 s[62:63], 34, v0
	v_cndmask_b32_e64 v97, v97, v1, s[64:65]
	v_cmp_gt_i32_e64 s[64:65], 3, v0
	v_cndmask_b32_e64 v113, v113, v1, s[66:67]
	v_cmp_gt_i32_e64 s[66:67], 35, v0
	v_cndmask_b32_e64 v98, v98, v1, s[60:61]
	v_cmp_gt_i32_e64 s[60:61], 8, v0
	v_cndmask_b32_e64 v114, v114, v1, s[62:63]
	v_cmp_gt_i32_e64 s[62:63], 40, v0
	v_cndmask_b32_e64 v99, v99, v1, s[64:65]
	v_cmp_gt_i32_e64 s[64:65], 9, v0
	v_cndmask_b32_e64 v115, v115, v1, s[66:67]
	v_cmp_gt_i32_e64 s[66:67], 41, v0
	v_cndmask_b32_e64 v100, v100, v1, s[60:61]
	v_cmp_gt_i32_e64 s[60:61], 10, v0
	v_cndmask_b32_e64 v116, v116, v1, s[62:63]
	v_cmp_gt_i32_e64 s[62:63], 42, v0
	v_cndmask_b32_e64 v101, v101, v1, s[64:65]
	v_cmp_gt_i32_e64 s[64:65], 11, v0
	v_cndmask_b32_e64 v117, v117, v1, s[66:67]
	v_cmp_gt_i32_e64 s[66:67], 43, v0
	v_cndmask_b32_e64 v102, v102, v1, s[60:61]
	v_cmp_gt_i32_e64 s[60:61], 16, v0
	v_cndmask_b32_e64 v118, v118, v1, s[62:63]
	v_cmp_gt_i32_e64 s[62:63], 48, v0
	v_cndmask_b32_e64 v103, v103, v1, s[64:65]
	v_cmp_gt_i32_e64 s[64:65], 17, v0
	v_cndmask_b32_e64 v119, v119, v1, s[66:67]
	v_cmp_gt_i32_e64 s[66:67], 49, v0
	v_cndmask_b32_e64 v104, v104, v1, s[60:61]
	v_cmp_gt_i32_e64 s[60:61], 18, v0
	v_cndmask_b32_e64 v120, v120, v1, s[62:63]
	v_cmp_gt_i32_e64 s[62:63], 50, v0
	v_cndmask_b32_e64 v105, v105, v1, s[64:65]
	v_cmp_gt_i32_e64 s[64:65], 19, v0
	v_cndmask_b32_e64 v121, v121, v1, s[66:67]
	v_cmp_gt_i32_e64 s[66:67], 51, v0
	v_cndmask_b32_e64 v106, v106, v1, s[60:61]
	v_cmp_gt_i32_e64 s[60:61], 24, v0
	v_cndmask_b32_e64 v122, v122, v1, s[62:63]
	v_cmp_gt_i32_e64 s[62:63], 56, v0
	v_cndmask_b32_e64 v107, v107, v1, s[64:65]
	v_cmp_gt_i32_e64 s[64:65], 25, v0
	v_cndmask_b32_e64 v123, v123, v1, s[66:67]
	v_cmp_gt_i32_e64 s[66:67], 57, v0
	v_cndmask_b32_e64 v108, v108, v1, s[60:61]
	v_cmp_gt_i32_e64 s[60:61], 26, v0
	v_cndmask_b32_e64 v124, v124, v1, s[62:63]
	v_cmp_gt_i32_e64 s[62:63], 58, v0
	v_cndmask_b32_e64 v109, v109, v1, s[64:65]
	v_cmp_gt_i32_e64 s[64:65], 27, v0
	v_cndmask_b32_e64 v125, v125, v1, s[66:67]
	v_cmp_gt_i32_e64 s[66:67], 59, v0
	v_cndmask_b32_e64 v110, v110, v1, s[60:61]
	s_nop 1
	v_cndmask_b32_e64 v126, v126, v1, s[62:63]
	v_cndmask_b32_e64 v111, v111, v1, s[64:65]
	v_cndmask_b32_e64 v127, v127, v1, s[66:67]
.Lat_nomask_936:
	ds_read_b64_tr_b16 v[200:201], v250 offset:8192
	ds_read_b64_tr_b16 v[202:203], v250 offset:8704
	ds_read_b64_tr_b16 v[204:205], v250 offset:12288
	ds_read_b64_tr_b16 v[206:207], v250 offset:12800
	s_waitcnt lgkmcnt(4)
	v_mfma_f32_32x32x16_bf16 v[32:47], v[176:179], v[192:195], v[32:47]
	v_max3_f32 v2, v96, v97, v112
	v_max3_f32 v4, v98, v99, v113
	v_max3_f32 v2, v2, v114, v115
	v_mfma_f32_32x32x16_bf16 v[48:63], v[176:179], v[196:199], v[48:63]
	v_max3_f32 v2, v2, v100, v101
	v_max3_f32 v4, v4, v102, v103
	v_max3_f32 v2, v2, v116, v117
	ds_read_b64_tr_b16 v[192:193], v250 offset:1024
	ds_read_b64_tr_b16 v[194:195], v250 offset:1536
	ds_read_b64_tr_b16 v[196:197], v250 offset:5120
	ds_read_b64_tr_b16 v[198:199], v250 offset:5632
	s_waitcnt lgkmcnt(4)
	v_mfma_f32_32x32x16_bf16 v[64:79], v[176:179], v[200:203], v[64:79]
	v_max3_f32 v4, v4, v118, v119
	v_max3_f32 v2, v2, v104, v105
	v_max3_f32 v4, v4, v106, v107
	v_mfma_f32_32x32x16_bf16 v[80:95], v[176:179], v[204:207], v[80:95]
	v_max3_f32 v2, v2, v120, v121
	v_max3_f32 v4, v4, v122, v123
	v_max3_f32 v2, v2, v108, v109
	ds_read_b64_tr_b16 v[200:201], v250 offset:9216
	ds_read_b64_tr_b16 v[202:203], v250 offset:9728
	ds_read_b64_tr_b16 v[204:205], v250 offset:13312
	ds_read_b64_tr_b16 v[206:207], v250 offset:13824
	s_waitcnt lgkmcnt(4)
	v_mfma_f32_32x32x16_bf16 v[32:47], v[180:183], v[192:195], v[32:47]
	v_max3_f32 v4, v4, v110, v111
	v_max3_f32 v2, v2, v124, v125
	v_max3_f32 v4, v4, v126, v127
	v_mfma_f32_32x32x16_bf16 v[48:63], v[180:183], v[196:199], v[48:63]
	v_max_f32_e32 v2, v2, v4
	v_mov_b32_e32 v4, v2
	s_nop 1
	v_permlane32_swap_b32_e32 v2, v4
	v_max_f32_e32 v2, v2, v4
	v_mov_b32_e32 v5, 0x41400000
	v_cmp_gt_f32_e32 vcc, v2, v5
	s_mov_b64 s[68:69], vcc
	s_cmp_lg_u64 vcc, 0
	s_cbranch_scc0 .Lat_noresc_855
	v_max_f32_e32 v4, 0, v2
	v_add_f32_e32 v248, v248, v4
	v_sub_f32_e32 v96, v96, v4
	v_sub_f32_e32 v97, v97, v4
	v_sub_f32_e32 v98, v98, v4
	v_sub_f32_e32 v99, v99, v4
	v_sub_f32_e32 v100, v100, v4
	v_sub_f32_e32 v101, v101, v4
	v_sub_f32_e32 v102, v102, v4
	v_sub_f32_e32 v103, v103, v4
	v_sub_f32_e32 v104, v104, v4
	v_sub_f32_e32 v105, v105, v4
	v_sub_f32_e32 v106, v106, v4
	v_sub_f32_e32 v107, v107, v4
	v_sub_f32_e32 v108, v108, v4
	v_sub_f32_e32 v109, v109, v4
	v_sub_f32_e32 v110, v110, v4
	v_sub_f32_e32 v111, v111, v4
	v_sub_f32_e32 v112, v112, v4
	v_sub_f32_e32 v113, v113, v4
	v_sub_f32_e32 v114, v114, v4
	v_sub_f32_e32 v115, v115, v4
	v_sub_f32_e32 v116, v116, v4
	v_sub_f32_e32 v117, v117, v4
	v_sub_f32_e32 v118, v118, v4
	v_sub_f32_e32 v119, v119, v4
	v_sub_f32_e32 v120, v120, v4
	v_sub_f32_e32 v121, v121, v4
	v_sub_f32_e32 v122, v122, v4
	v_sub_f32_e32 v123, v123, v4
	v_sub_f32_e32 v124, v124, v4
	v_sub_f32_e32 v125, v125, v4
	v_sub_f32_e32 v126, v126, v4
	v_sub_f32_e32 v127, v127, v4
	v_xor_b32_e32 v5, 0x80000000, v248
	v_mov_b32_e32 v160, v5
	v_mov_b32_e32 v161, v5
	v_mov_b32_e32 v162, v5
	v_mov_b32_e32 v163, v5
	v_mov_b32_e32 v164, v5
	v_mov_b32_e32 v165, v5
	v_mov_b32_e32 v166, v5
	v_mov_b32_e32 v167, v5
	v_mov_b32_e32 v168, v5
	v_mov_b32_e32 v169, v5
	v_mov_b32_e32 v170, v5
	v_mov_b32_e32 v171, v5
	v_mov_b32_e32 v172, v5
	v_mov_b32_e32 v173, v5
	v_mov_b32_e32 v174, v5
	v_mov_b32_e32 v175, v5
	v_xor_b32_e32 v6, 0x80000000, v4
	v_exp_f32_e32 v6, v6
	s_nop 0
	v_mul_f32_e32 v247, v247, v6
	v_and_b32_e32 v7, 31, v237
	v_lshl_add_u32 v7, v7, 2, v249
	v_cmp_eq_u32_e32 vcc, 0, v252
	s_and_saveexec_b64 s[60:61], vcc
	ds_write_b32 v7, v6
	s_or_b64 exec, exec, s[60:61]
.Lat_noresc_855:
	v_add_u32_e32 v3, s58, v244
	ds_read_b64_tr_b16 v[192:193], v250 offset:2048
	ds_read_b64_tr_b16 v[194:195], v250 offset:2560
	ds_read_b64_tr_b16 v[196:197], v250 offset:6144
	ds_read_b64_tr_b16 v[198:199], v250 offset:6656
	s_waitcnt lgkmcnt(4)
	v_mfma_f32_32x32x16_bf16 v[64:79], v[180:183], v[200:203], v[64:79]
	v_exp_f32_e32 v96, v96
	v_exp_f32_e32 v97, v97
	v_exp_f32_e32 v98, v98
	ds_read_b128 v[208:211], v3
	v_mfma_f32_32x32x16_bf16 v[80:95], v[180:183], v[204:207], v[80:95]
	v_exp_f32_e32 v99, v99
	v_exp_f32_e32 v100, v100
	v_exp_f32_e32 v101, v101
	ds_read_b128 v[212:215], v3 offset:512
	ds_read_b64_tr_b16 v[200:201], v250 offset:10240
	ds_read_b64_tr_b16 v[202:203], v250 offset:10752
	ds_read_b64_tr_b16 v[204:205], v250 offset:14336
	ds_read_b64_tr_b16 v[206:207], v250 offset:14848
	s_waitcnt lgkmcnt(6)
	v_mfma_f32_32x32x16_bf16 v[32:47], v[184:187], v[192:195], v[32:47]
	v_exp_f32_e32 v102, v102
	v_exp_f32_e32 v103, v103
	v_exp_f32_e32 v104, v104
	ds_read_b128 v[216:219], v3 offset:2048
	v_mfma_f32_32x32x16_bf16 v[48:63], v[184:187], v[196:199], v[48:63]
	v_exp_f32_e32 v105, v105
	v_exp_f32_e32 v106, v106
	v_exp_f32_e32 v107, v107
	ds_read_b128 v[220:223], v3 offset:2560
	ds_read_b64_tr_b16 v[192:193], v250 offset:3072
	ds_read_b64_tr_b16 v[194:195], v250 offset:3584
	ds_read_b64_tr_b16 v[196:197], v250 offset:7168
	ds_read_b64_tr_b16 v[198:199], v250 offset:7680
	s_waitcnt lgkmcnt(6)
	v_mfma_f32_32x32x16_bf16 v[64:79], v[184:187], v[200:203], v[64:79]
	v_exp_f32_e32 v108, v108
	v_exp_f32_e32 v109, v109
	v_exp_f32_e32 v110, v110
	ds_read_b128 v[224:227], v3 offset:4096
	v_mfma_f32_32x32x16_bf16 v[80:95], v[184:187], v[204:207], v[80:95]
	v_exp_f32_e32 v111, v111
	v_exp_f32_e32 v112, v112
	v_exp_f32_e32 v113, v113
	ds_read_b128 v[228:231], v3 offset:4608
	ds_read_b64_tr_b16 v[200:201], v250 offset:11264
	ds_read_b64_tr_b16 v[202:203], v250 offset:11776
	ds_read_b64_tr_b16 v[204:205], v250 offset:15360
	ds_read_b64_tr_b16 v[206:207], v250 offset:15872
	s_waitcnt lgkmcnt(6)
	v_mfma_f32_32x32x16_bf16 v[32:47], v[188:191], v[192:195], v[32:47]
	v_exp_f32_e32 v114, v114
	v_exp_f32_e32 v115, v115
	v_exp_f32_e32 v116, v116
	ds_read_b128 v[232:235], v3 offset:6144
	v_mfma_f32_32x32x16_bf16 v[48:63], v[188:191], v[196:199], v[48:63]
	v_exp_f32_e32 v117, v117
	v_exp_f32_e32 v118, v118
	v_exp_f32_e32 v119, v119
	ds_read_b128 v[240:243], v3 offset:6656
	s_waitcnt lgkmcnt(2)
	v_mfma_f32_32x32x16_bf16 v[64:79], v[188:191], v[200:203], v[64:79]
	v_exp_f32_e32 v120, v120
	v_exp_f32_e32 v121, v121
	v_exp_f32_e32 v122, v122
	v_exp_f32_e32 v123, v123
	v_mfma_f32_32x32x16_bf16 v[80:95], v[188:191], v[204:207], v[80:95]
	v_exp_f32_e32 v124, v124
	v_exp_f32_e32 v125, v125
	v_exp_f32_e32 v126, v126
	v_exp_f32_e32 v127, v127
	s_waitcnt vmcnt(3) lgkmcnt(0)
	s_barrier
	s_cmp_lg_u64 s[68:69], 0
	s_cbranch_scc0 .Lat_norescO_855
	v_lshl_add_u32 v250, v252, 4, v249
	ds_read_b128 v[0:3], v250 offset:0
	ds_read_b128 v[4:7], v250 offset:32
	ds_read_b128 v[8:11], v250 offset:64
	ds_read_b128 v[12:15], v250 offset:96
	s_nop 7
	s_nop 7
	s_waitcnt lgkmcnt(0)
	v_mul_f32_e32 v32, v32, v0
	v_mul_f32_e32 v33, v33, v1
	v_mul_f32_e32 v34, v34, v2
	v_mul_f32_e32 v35, v35, v3
	v_mul_f32_e32 v36, v36, v4
	v_mul_f32_e32 v37, v37, v5
	v_mul_f32_e32 v38, v38, v6
	v_mul_f32_e32 v39, v39, v7
	v_mul_f32_e32 v40, v40, v8
	v_mul_f32_e32 v41, v41, v9
	v_mul_f32_e32 v42, v42, v10
	v_mul_f32_e32 v43, v43, v11
	v_mul_f32_e32 v44, v44, v12
	v_mul_f32_e32 v45, v45, v13
	v_mul_f32_e32 v46, v46, v14
	v_mul_f32_e32 v47, v47, v15
	v_mul_f32_e32 v48, v48, v0
	v_mul_f32_e32 v49, v49, v1
	v_mul_f32_e32 v50, v50, v2
	v_mul_f32_e32 v51, v51, v3
	v_mul_f32_e32 v52, v52, v4
	v_mul_f32_e32 v53, v53, v5
	v_mul_f32_e32 v54, v54, v6
	v_mul_f32_e32 v55, v55, v7
	v_mul_f32_e32 v56, v56, v8
	v_mul_f32_e32 v57, v57, v9
	v_mul_f32_e32 v58, v58, v10
	v_mul_f32_e32 v59, v59, v11
	v_mul_f32_e32 v60, v60, v12
	v_mul_f32_e32 v61, v61, v13
	v_mul_f32_e32 v62, v62, v14
	v_mul_f32_e32 v63, v63, v15
	v_mul_f32_e32 v64, v64, v0
	v_mul_f32_e32 v65, v65, v1
	v_mul_f32_e32 v66, v66, v2
	v_mul_f32_e32 v67, v67, v3
	v_mul_f32_e32 v68, v68, v4
	v_mul_f32_e32 v69, v69, v5
	v_mul_f32_e32 v70, v70, v6
	v_mul_f32_e32 v71, v71, v7
	v_mul_f32_e32 v72, v72, v8
	v_mul_f32_e32 v73, v73, v9
	v_mul_f32_e32 v74, v74, v10
	v_mul_f32_e32 v75, v75, v11
	v_mul_f32_e32 v76, v76, v12
	v_mul_f32_e32 v77, v77, v13
	v_mul_f32_e32 v78, v78, v14
	v_mul_f32_e32 v79, v79, v15
	v_mul_f32_e32 v80, v80, v0
	v_mul_f32_e32 v81, v81, v1
	v_mul_f32_e32 v82, v82, v2
	v_mul_f32_e32 v83, v83, v3
	v_mul_f32_e32 v84, v84, v4
	v_mul_f32_e32 v85, v85, v5
	v_mul_f32_e32 v86, v86, v6
	v_mul_f32_e32 v87, v87, v7
	v_mul_f32_e32 v88, v88, v8
	v_mul_f32_e32 v89, v89, v9
	v_mul_f32_e32 v90, v90, v10
	v_mul_f32_e32 v91, v91, v11
	v_mul_f32_e32 v92, v92, v12
	v_mul_f32_e32 v93, v93, v13
	v_mul_f32_e32 v94, v94, v14
	v_mul_f32_e32 v95, v95, v15

.Lat_drain:
	v_add_f32_e32 v247, v247, v128
	v_add_f32_e32 v247, v247, v129
	v_add_f32_e32 v247, v247, v130
	v_add_f32_e32 v247, v247, v131
	v_cvt_pk_bf16_f32 v176, v128, v129
	v_cvt_pk_bf16_f32 v177, v130, v131
	v_add_f32_e32 v247, v247, v132
	v_add_f32_e32 v247, v247, v133
	v_add_f32_e32 v247, v247, v134
	v_add_f32_e32 v247, v247, v135
	v_cvt_pk_bf16_f32 v178, v132, v133
	v_cvt_pk_bf16_f32 v179, v134, v135
	v_add_f32_e32 v247, v247, v136
	v_add_f32_e32 v247, v247, v137
	v_add_f32_e32 v247, v247, v138
	v_add_f32_e32 v247, v247, v139
	v_cvt_pk_bf16_f32 v180, v136, v137
	v_cvt_pk_bf16_f32 v181, v138, v139
	v_add_f32_e32 v247, v247, v140
	v_add_f32_e32 v247, v247, v141
	v_add_f32_e32 v247, v247, v142
	v_add_f32_e32 v247, v247, v143
	v_cvt_pk_bf16_f32 v182, v140, v141
	v_cvt_pk_bf16_f32 v183, v142, v143
	v_add_f32_e32 v247, v247, v144
	v_add_f32_e32 v247, v247, v145
	v_add_f32_e32 v247, v247, v146
	v_add_f32_e32 v247, v247, v147
	v_cvt_pk_bf16_f32 v184, v144, v145
	v_cvt_pk_bf16_f32 v185, v146, v147
	v_add_f32_e32 v247, v247, v148
	v_add_f32_e32 v247, v247, v149
	v_add_f32_e32 v247, v247, v150
	v_add_f32_e32 v247, v247, v151
	v_cvt_pk_bf16_f32 v186, v148, v149
	v_cvt_pk_bf16_f32 v187, v150, v151
	v_add_f32_e32 v247, v247, v152
	v_add_f32_e32 v247, v247, v153
	v_add_f32_e32 v247, v247, v154
	v_add_f32_e32 v247, v247, v155
	v_cvt_pk_bf16_f32 v188, v152, v153
	v_cvt_pk_bf16_f32 v189, v154, v155
	v_add_f32_e32 v247, v247, v156
	v_add_f32_e32 v247, v247, v157
	v_add_f32_e32 v247, v247, v158
	v_add_f32_e32 v247, v247, v159
	v_cvt_pk_bf16_f32 v190, v156, v157
	v_cvt_pk_bf16_f32 v191, v158, v159
	s_lshl_b32 s60, s56, 1
	v_add_u32_e32 v250, s60, v245
	ds_read_b64_tr_b16 v[192:193], v250 offset:0
	ds_read_b64_tr_b16 v[194:195], v250 offset:512
	ds_read_b64_tr_b16 v[196:197], v250 offset:4096
	ds_read_b64_tr_b16 v[198:199], v250 offset:4608
	ds_read_b64_tr_b16 v[200:201], v250 offset:8192
	ds_read_b64_tr_b16 v[202:203], v250 offset:8704
	ds_read_b64_tr_b16 v[204:205], v250 offset:12288
	ds_read_b64_tr_b16 v[206:207], v250 offset:12800
	s_waitcnt lgkmcnt(6)
	v_mfma_f32_32x32x16_bf16 v[32:47], v[176:179], v[192:195], v[32:47]
	ds_read_b64_tr_b16 v[192:193], v250 offset:1024
	ds_read_b64_tr_b16 v[194:195], v250 offset:1536
	s_waitcnt lgkmcnt(6)
	v_mfma_f32_32x32x16_bf16 v[48:63], v[176:179], v[196:199], v[48:63]
	ds_read_b64_tr_b16 v[196:197], v250 offset:5120
	ds_read_b64_tr_b16 v[198:199], v250 offset:5632
	s_waitcnt lgkmcnt(6)
	v_mfma_f32_32x32x16_bf16 v[64:79], v[176:179], v[200:203], v[64:79]
	ds_read_b64_tr_b16 v[200:201], v250 offset:9216
	ds_read_b64_tr_b16 v[202:203], v250 offset:9728
	s_waitcnt lgkmcnt(6)
	v_mfma_f32_32x32x16_bf16 v[80:95], v[176:179], v[204:207], v[80:95]
	ds_read_b64_tr_b16 v[204:205], v250 offset:13312
	ds_read_b64_tr_b16 v[206:207], v250 offset:13824
	s_waitcnt lgkmcnt(6)
	v_mfma_f32_32x32x16_bf16 v[32:47], v[180:183], v[192:195], v[32:47]
	ds_read_b64_tr_b16 v[192:193], v250 offset:2048
	ds_read_b64_tr_b16 v[194:195], v250 offset:2560
	s_waitcnt lgkmcnt(6)
	v_mfma_f32_32x32x16_bf16 v[48:63], v[180:183], v[196:199], v[48:63]
	ds_read_b64_tr_b16 v[196:197], v250 offset:6144
	ds_read_b64_tr_b16 v[198:199], v250 offset:6656
	s_waitcnt lgkmcnt(6)
	v_mfma_f32_32x32x16_bf16 v[64:79], v[180:183], v[200:203], v[64:79]
	ds_read_b64_tr_b16 v[200:201], v250 offset:10240
	ds_read_b64_tr_b16 v[202:203], v250 offset:10752
	s_waitcnt lgkmcnt(6)
	v_mfma_f32_32x32x16_bf16 v[80:95], v[180:183], v[204:207], v[80:95]
	ds_read_b64_tr_b16 v[204:205], v250 offset:14336
	ds_read_b64_tr_b16 v[206:207], v250 offset:14848
	s_waitcnt lgkmcnt(6)
	v_mfma_f32_32x32x16_bf16 v[32:47], v[184:187], v[192:195], v[32:47]
	ds_read_b64_tr_b16 v[192:193], v250 offset:3072
	ds_read_b64_tr_b16 v[194:195], v250 offset:3584
	s_waitcnt lgkmcnt(6)
	v_mfma_f32_32x32x16_bf16 v[48:63], v[184:187], v[196:199], v[48:63]
	ds_read_b64_tr_b16 v[196:197], v250 offset:7168
	ds_read_b64_tr_b16 v[198:199], v250 offset:7680
	s_waitcnt lgkmcnt(6)
	v_mfma_f32_32x32x16_bf16 v[64:79], v[184:187], v[200:203], v[64:79]
	ds_read_b64_tr_b16 v[200:201], v250 offset:11264
	ds_read_b64_tr_b16 v[202:203], v250 offset:11776
	s_waitcnt lgkmcnt(6)
	v_mfma_f32_32x32x16_bf16 v[80:95], v[184:187], v[204:207], v[80:95]
	ds_read_b64_tr_b16 v[204:205], v250 offset:15360
	ds_read_b64_tr_b16 v[206:207], v250 offset:15872
	s_waitcnt lgkmcnt(6)
	v_mfma_f32_32x32x16_bf16 v[32:47], v[188:191], v[192:195], v[32:47]
	s_waitcnt lgkmcnt(4)
	v_mfma_f32_32x32x16_bf16 v[48:63], v[188:191], v[196:199], v[48:63]
	s_waitcnt lgkmcnt(2)
	v_mfma_f32_32x32x16_bf16 v[64:79], v[188:191], v[200:203], v[64:79]
	s_waitcnt lgkmcnt(0)
	v_mfma_f32_32x32x16_bf16 v[80:95], v[188:191], v[204:207], v[80:95]
	v_mov_b32_e32 v250, v247
	v_mov_b32_e32 v251, v247
	s_nop 1
	v_permlane32_swap_b32_e32 v250, v251
	v_add_f32_e32 v250, v250, v251
	s_waitcnt vmcnt(0) lgkmcnt(0)
	s_barrier
	v_and_b32_e32 v244, 31, v237
	v_lshl_add_u32 v244, v244, 2, v249
	v_cmp_eq_u32_e32 vcc, 0, v252
	s_and_saveexec_b64 s[60:61], vcc
	ds_write_b32 v244, v250 offset:128
	s_or_b64 exec, exec, s[60:61]
	s_waitcnt lgkmcnt(0)
	v_lshl_add_u32 v250, v252, 4, v249
	ds_read_b128 v[0:3], v250 offset:128
	ds_read_b128 v[4:7], v250 offset:160
	ds_read_b128 v[8:11], v250 offset:192
	ds_read_b128 v[12:15], v250 offset:224
	s_waitcnt lgkmcnt(0)
	v_rcp_f32_e32 v0, v0
	v_rcp_f32_e32 v1, v1
	v_rcp_f32_e32 v2, v2
	v_rcp_f32_e32 v3, v3
	v_rcp_f32_e32 v4, v4
	v_rcp_f32_e32 v5, v5
	v_rcp_f32_e32 v6, v6
	v_rcp_f32_e32 v7, v7
	v_rcp_f32_e32 v8, v8
	v_rcp_f32_e32 v9, v9
	v_rcp_f32_e32 v10, v10
	v_rcp_f32_e32 v11, v11
	v_rcp_f32_e32 v12, v12
	v_rcp_f32_e32 v13, v13
	v_rcp_f32_e32 v14, v14
	v_rcp_f32_e32 v15, v15
	s_nop 7
	s_nop 7
	s_lshl_b32 s60, s47, 13
	v_and_b32_e32 v250, 31, v237
	v_lshlrev_b32_e32 v250, 1, v250
	v_add_u32_e32 v250, s60, v250
	v_lshlrev_b32_e32 v251, 10, v252
	v_add_u32_e32 v250, v250, v251
	v_mul_f32_e32 v251, v32, v0
	v_cvt_pk_bf16_f32 v251, v251, v251
	ds_write_b16 v250, v251 offset:0
	v_mul_f32_e32 v251, v48, v0
	v_cvt_pk_bf16_f32 v251, v251, v251
	ds_write_b16 v250, v251 offset:64
	v_mul_f32_e32 v251, v64, v0
	v_cvt_pk_bf16_f32 v251, v251, v251
	ds_write_b16 v250, v251 offset:128
	v_mul_f32_e32 v251, v80, v0
	v_cvt_pk_bf16_f32 v251, v251, v251
	ds_write_b16 v250, v251 offset:192
	v_mul_f32_e32 v251, v33, v1
	v_cvt_pk_bf16_f32 v251, v251, v251
	ds_write_b16 v250, v251 offset:256
	v_mul_f32_e32 v251, v49, v1
	v_cvt_pk_bf16_f32 v251, v251, v251
	ds_write_b16 v250, v251 offset:320
	v_mul_f32_e32 v251, v65, v1
	v_cvt_pk_bf16_f32 v251, v251, v251
	ds_write_b16 v250, v251 offset:384
	v_mul_f32_e32 v251, v81, v1
	v_cvt_pk_bf16_f32 v251, v251, v251
	ds_write_b16 v250, v251 offset:448
	v_mul_f32_e32 v251, v34, v2
	v_cvt_pk_bf16_f32 v251, v251, v251
	ds_write_b16 v250, v251 offset:512
	v_mul_f32_e32 v251, v50, v2
	v_cvt_pk_bf16_f32 v251, v251, v251
	ds_write_b16 v250, v251 offset:576
	v_mul_f32_e32 v251, v66, v2
	v_cvt_pk_bf16_f32 v251, v251, v251
	ds_write_b16 v250, v251 offset:640
	v_mul_f32_e32 v251, v82, v2
	v_cvt_pk_bf16_f32 v251, v251, v251
	ds_write_b16 v250, v251 offset:704
	v_mul_f32_e32 v251, v35, v3
	v_cvt_pk_bf16_f32 v251, v251, v251
	ds_write_b16 v250, v251 offset:768
	v_mul_f32_e32 v251, v51, v3
	v_cvt_pk_bf16_f32 v251, v251, v251
	ds_write_b16 v250, v251 offset:832
	v_mul_f32_e32 v251, v67, v3
	v_cvt_pk_bf16_f32 v251, v251, v251
	ds_write_b16 v250, v251 offset:896
	v_mul_f32_e32 v251, v83, v3
	v_cvt_pk_bf16_f32 v251, v251, v251
	ds_write_b16 v250, v251 offset:960
	v_mul_f32_e32 v251, v36, v4
	v_cvt_pk_bf16_f32 v251, v251, v251
	ds_write_b16 v250, v251 offset:2048
	v_mul_f32_e32 v251, v52, v4
	v_cvt_pk_bf16_f32 v251, v251, v251
	ds_write_b16 v250, v251 offset:2112
	v_mul_f32_e32 v251, v68, v4
	v_cvt_pk_bf16_f32 v251, v251, v251
	ds_write_b16 v250, v251 offset:2176
	v_mul_f32_e32 v251, v84, v4
	v_cvt_pk_bf16_f32 v251, v251, v251
	ds_write_b16 v250, v251 offset:2240
	v_mul_f32_e32 v251, v37, v5
	v_cvt_pk_bf16_f32 v251, v251, v251
	ds_write_b16 v250, v251 offset:2304
	v_mul_f32_e32 v251, v53, v5
	v_cvt_pk_bf16_f32 v251, v251, v251
	ds_write_b16 v250, v251 offset:2368
	v_mul_f32_e32 v251, v69, v5
	v_cvt_pk_bf16_f32 v251, v251, v251
	ds_write_b16 v250, v251 offset:2432
	v_mul_f32_e32 v251, v85, v5
	v_cvt_pk_bf16_f32 v251, v251, v251
	ds_write_b16 v250, v251 offset:2496
	v_mul_f32_e32 v251, v38, v6
	v_cvt_pk_bf16_f32 v251, v251, v251
	ds_write_b16 v250, v251 offset:2560
	v_mul_f32_e32 v251, v54, v6
	v_cvt_pk_bf16_f32 v251, v251, v251
	ds_write_b16 v250, v251 offset:2624
	v_mul_f32_e32 v251, v70, v6
	v_cvt_pk_bf16_f32 v251, v251, v251
	ds_write_b16 v250, v251 offset:2688
	v_mul_f32_e32 v251, v86, v6
	v_cvt_pk_bf16_f32 v251, v251, v251
	ds_write_b16 v250, v251 offset:2752
	v_mul_f32_e32 v251, v39, v7
	v_cvt_pk_bf16_f32 v251, v251, v251
	ds_write_b16 v250, v251 offset:2816
	v_mul_f32_e32 v251, v55, v7
	v_cvt_pk_bf16_f32 v251, v251, v251
	ds_write_b16 v250, v251 offset:2880
	v_mul_f32_e32 v251, v71, v7
	v_cvt_pk_bf16_f32 v251, v251, v251
	ds_write_b16 v250, v251 offset:2944
	v_mul_f32_e32 v251, v87, v7
	v_cvt_pk_bf16_f32 v251, v251, v251
	ds_write_b16 v250, v251 offset:3008
	v_mul_f32_e32 v251, v40, v8
	v_cvt_pk_bf16_f32 v251, v251, v251
	ds_write_b16 v250, v251 offset:4096
	v_mul_f32_e32 v251, v56, v8
	v_cvt_pk_bf16_f32 v251, v251, v251
	ds_write_b16 v250, v251 offset:4160
	v_mul_f32_e32 v251, v72, v8
	v_cvt_pk_bf16_f32 v251, v251, v251
	ds_write_b16 v250, v251 offset:4224
	v_mul_f32_e32 v251, v88, v8
	v_cvt_pk_bf16_f32 v251, v251, v251
	ds_write_b16 v250, v251 offset:4288
	v_mul_f32_e32 v251, v41, v9
	v_cvt_pk_bf16_f32 v251, v251, v251
	ds_write_b16 v250, v251 offset:4352
	v_mul_f32_e32 v251, v57, v9
	v_cvt_pk_bf16_f32 v251, v251, v251
	ds_write_b16 v250, v251 offset:4416
	v_mul_f32_e32 v251, v73, v9
	v_cvt_pk_bf16_f32 v251, v251, v251
	ds_write_b16 v250, v251 offset:4480
	v_mul_f32_e32 v251, v89, v9
	v_cvt_pk_bf16_f32 v251, v251, v251
	ds_write_b16 v250, v251 offset:4544
	v_mul_f32_e32 v251, v42, v10
	v_cvt_pk_bf16_f32 v251, v251, v251
	ds_write_b16 v250, v251 offset:4608
	v_mul_f32_e32 v251, v58, v10
	v_cvt_pk_bf16_f32 v251, v251, v251
	ds_write_b16 v250, v251 offset:4672
	v_mul_f32_e32 v251, v74, v10
	v_cvt_pk_bf16_f32 v251, v251, v251
	ds_write_b16 v250, v251 offset:4736
	v_mul_f32_e32 v251, v90, v10
	v_cvt_pk_bf16_f32 v251, v251, v251
	ds_write_b16 v250, v251 offset:4800
	v_mul_f32_e32 v251, v43, v11
	v_cvt_pk_bf16_f32 v251, v251, v251
	ds_write_b16 v250, v251 offset:4864
	v_mul_f32_e32 v251, v59, v11
	v_cvt_pk_bf16_f32 v251, v251, v251
	ds_write_b16 v250, v251 offset:4928
	v_mul_f32_e32 v251, v75, v11
	v_cvt_pk_bf16_f32 v251, v251, v251
	ds_write_b16 v250, v251 offset:4992
	v_mul_f32_e32 v251, v91, v11
	v_cvt_pk_bf16_f32 v251, v251, v251
	ds_write_b16 v250, v251 offset:5056
	v_mul_f32_e32 v251, v44, v12
	v_cvt_pk_bf16_f32 v251, v251, v251
	ds_write_b16 v250, v251 offset:6144
	v_mul_f32_e32 v251, v60, v12
	v_cvt_pk_bf16_f32 v251, v251, v251
	ds_write_b16 v250, v251 offset:6208
	v_mul_f32_e32 v251, v76, v12
	v_cvt_pk_bf16_f32 v251, v251, v251
	ds_write_b16 v250, v251 offset:6272
	v_mul_f32_e32 v251, v92, v12
	v_cvt_pk_bf16_f32 v251, v251, v251
	ds_write_b16 v250, v251 offset:6336
	v_mul_f32_e32 v251, v45, v13
	v_cvt_pk_bf16_f32 v251, v251, v251
	ds_write_b16 v250, v251 offset:6400
	v_mul_f32_e32 v251, v61, v13
	v_cvt_pk_bf16_f32 v251, v251, v251
	ds_write_b16 v250, v251 offset:6464
	v_mul_f32_e32 v251, v77, v13
	v_cvt_pk_bf16_f32 v251, v251, v251
	ds_write_b16 v250, v251 offset:6528
	v_mul_f32_e32 v251, v93, v13
	v_cvt_pk_bf16_f32 v251, v251, v251
	ds_write_b16 v250, v251 offset:6592
	v_mul_f32_e32 v251, v46, v14
	v_cvt_pk_bf16_f32 v251, v251, v251
	ds_write_b16 v250, v251 offset:6656
	v_mul_f32_e32 v251, v62, v14
	v_cvt_pk_bf16_f32 v251, v251, v251
	ds_write_b16 v250, v251 offset:6720
	v_mul_f32_e32 v251, v78, v14
	v_cvt_pk_bf16_f32 v251, v251, v251
	ds_write_b16 v250, v251 offset:6784
	v_mul_f32_e32 v251, v94, v14
	v_cvt_pk_bf16_f32 v251, v251, v251
	ds_write_b16 v250, v251 offset:6848
	v_mul_f32_e32 v251, v47, v15
	v_cvt_pk_bf16_f32 v251, v251, v251
	ds_write_b16 v250, v251 offset:6912
	v_mul_f32_e32 v251, v63, v15
	v_cvt_pk_bf16_f32 v251, v251, v251
	ds_write_b16 v250, v251 offset:6976
	v_mul_f32_e32 v251, v79, v15
	v_cvt_pk_bf16_f32 v251, v251, v251
	ds_write_b16 v250, v251 offset:7040
	v_mul_f32_e32 v251, v95, v15
	v_cvt_pk_bf16_f32 v251, v251, v251
	ds_write_b16 v250, v251 offset:7104
	s_waitcnt lgkmcnt(0)
	v_lshrrev_b32_e32 v251, 4, v237
	v_and_b32_e32 v244, 15, v237
	v_lshlrev_b32_e32 v245, 8, v251
	v_lshl_or_b32 v245, v244, 4, v245
	v_add_u32_e32 v245, s60, v245
	v_lshlrev_b32_e32 v246, 11, v251
	v_lshl_or_b32 v246, v244, 4, v246
	ds_read_b128 v[16:19], v245 offset:0
	s_waitcnt lgkmcnt(0)
	global_store_dwordx4 v246, v[16:19], s[52:53]
	v_add_u32_e32 v246, 0x2000, v246
	s_nop 1
	ds_read_b128 v[16:19], v245 offset:1024
	s_waitcnt lgkmcnt(0)
	global_store_dwordx4 v246, v[16:19], s[52:53]
	v_add_u32_e32 v246, 0x2000, v246
	s_nop 1
	ds_read_b128 v[16:19], v245 offset:2048
	s_waitcnt lgkmcnt(0)
	global_store_dwordx4 v246, v[16:19], s[52:53]
	v_add_u32_e32 v246, 0x2000, v246
	s_nop 1
	ds_read_b128 v[16:19], v245 offset:3072
	s_waitcnt lgkmcnt(0)
	global_store_dwordx4 v246, v[16:19], s[52:53]
	v_add_u32_e32 v246, 0x2000, v246
	s_nop 1
	ds_read_b128 v[16:19], v245 offset:4096
	s_waitcnt lgkmcnt(0)
	global_store_dwordx4 v246, v[16:19], s[52:53]
	v_add_u32_e32 v246, 0x2000, v246
	s_nop 1
	ds_read_b128 v[16:19], v245 offset:5120
	s_waitcnt lgkmcnt(0)
	global_store_dwordx4 v246, v[16:19], s[52:53]
	v_add_u32_e32 v246, 0x2000, v246
	s_nop 1
	ds_read_b128 v[16:19], v245 offset:6144
	s_waitcnt lgkmcnt(0)
	global_store_dwordx4 v246, v[16:19], s[52:53]
	v_add_u32_e32 v246, 0x2000, v246
	s_nop 1
	ds_read_b128 v[16:19], v245 offset:7168
	s_waitcnt lgkmcnt(0)
	global_store_dwordx4 v246, v[16:19], s[52:53]
	v_add_u32_e32 v246, 0x2000, v246
	s_nop 1
	s_waitcnt lgkmcnt(0)
	s_barrier
